# MLA KV loop: fewer issued instructions per tile (-29 of 200): unconditional K loads, merged waitcnts, max tree without canonicalize, toggled LDS offsets, V fragments via ds_read_b128
# speedup vs baseline: 1.0338x; 1.0338x over previous
; #define LAS __attribute__((address_space(3)))
; __device__ __forceinline__ int lane_id_() { return (int)__builtin_amdgcn_mbcnt_hi(~0u, __builtin_amdgcn_mbcnt_lo(~0u, 0u)); }
; #define PH(n) if constexpr ((PHASE_MASK >> (n)) & 1)
; template <int DQK, int DV, int RH, bool NEGM> ...
;     constexpr int CH = DQK / 8, KCH = 64 * CH, NKL = (KCH + 511) / 512, VCH = DV * 8, NVL = VCH / 512;
;     constexpr int KROWB = (DQK + 8) * 2, KBUF = 64 * KROWB, VROWB = 136, VBUF = DV * VROWB;
;     int lane_ = lane_id_(); asm volatile("" : "+v"(lane_));
;     const int lane = lane_, wid = wave_, tid = wave_ * 64 + lane, r32 = lane & 31, hi = lane >> 5;
;     const bool grpB = false;
;     LAS unsigned char* Kl = lds; LAS unsigned char* Vl = lds + 2 * KBUF;
; __global__ void __launch_bounds__(512, 2) fwd_mega(Args a) {
;     ...
;         PH(11) for (int L = vcu; L < 8 * 8 * 16; L += G) {
;             const int qb = L & 15, bh = L >> 4, b = bh >> 3, h = bh & 7; const size_t row0 = (size_t)b * SEQ + qb * 256;
;             attn_unit<96, 64, 1, true>(lds, Qb + row0 * 768 + h * 96, 768, Kbuf + (size_t)b * SEQ * 768 + h * 96, 768,
;                               Vt + (size_t)(b * 512 + h * 64) * 4096, 4096, SEQ, P + row0 * PW + PC_ZMLA + h * 64, P + row0 * PW + PC_ZMLA + h * 64, PW, wave);
.LBB0_859:
	s_cmpk_gt_i32 s87, 0x3ff
	s_cbranch_scc1 .LBB0_895
	s_add_u32 s3, s6, 0x5000000
	s_addc_u32 s24, s7, 0
	s_add_u32 s25, s6, 0x2000000
	s_addc_u32 s48, s7, 0
	s_add_u32 s49, s10, 0x17000000
	s_addc_u32 s50, s11, 0
	v_add_u32_e32 v0, 64, v187
	s_add_u32 s28, s6, 0x2030000
	v_cmp_lt_i32_e32 vcc, v185, v0
	s_addc_u32 s29, s7, 0
	s_add_u32 s30, s10, 0x17000100
	v_cndmask_b32_e32 v0, v184, v185, vcc
	v_lshlrev_b32_e32 v162, 2, v0
	s_addc_u32 s31, s11, 0
	s_movk_i32 s51, 0x600
	v_mov_b32_e32 v149, 0
	s_movk_i32 s52, 0x300
	s_mov_b32 s53, 0x2aaaaaab
	s_movk_i32 s54, 0xff
	s_movk_i32 s55, 0x100
	s_movk_i32 s56, 0xd0
	s_movk_i32 s57, 0x90
	s_mov_b32 s58, 0xaaaaaaab
	s_mov_b32 s59, 0x41000000
	s_mov_b64 s[34:35], 0x18000
	s_mov_b64 s[36:37], 0x80
	s_movk_i32 s60, 0x2800
	v_mov_b32_e32 v163, 0xc0
	s_mov_b32 s61, s87
	s_branch .LBB0_863

; template <int DQK, int DV, int RH, bool NEGM> ...
;     ...
;     AT_GLOAD(0); AT_LSTORE(0, 0); __syncthreads();
.LBB0_871:
	s_or_b64 exec, exec, s[44:45]
	v_mul_lo_u32 v5, v8, s57
	v_and_b32_e32 v241, 6, v132
	v_lshlrev_b32_e32 v241, 4, v241
	v_and_b32_e32 v242, 1, v132
	v_lshl_or_b32 v241, v242, 3, v241
	v_add3_u32 v166, 0, v5, v241
	v_add_u32_e32 v5, 0x6800, v166
	v_add_u32_e32 v243, 0x6800, v166
	s_waitcnt vmcnt(0)
	ds_write2_b64 v5, v[0:1], v[2:3] offset1:2
	s_waitcnt lgkmcnt(0)
	s_barrier
	s_and_saveexec_b64 s[44:45], s[6:7]
	s_cbranch_execz .LBB0_873
	v_add_u32_e32 v0, v136, v135
	v_mul_lo_u32 v1, v0, 12
	v_sub_u32_e32 v2, v133, v1
	v_add_u32_e32 v3, 64, v0
	v_mov_b64_e32 v[0:1], s[42:43]
	v_lshlrev_b32_e32 v2, 3, v2
	v_mad_i64_i32 v[0:1], s[62:63], v3, s51, v[0:1]
	v_ashrrev_i32_e32 v3, 31, v2
	v_lshl_add_u64 v[0:1], v[2:3], 1, v[0:1]
	global_load_dwordx4 v[104:107], v[0:1], off

.LBB0_875:
	s_or_b64 exec, exec, s[44:45]
	global_load_dwordx4 v[74:77], v[6:7], off offset:128
	v_mul_u32_u24_e32 v0, 0xd0, v134
	v_lshlrev_b32_e32 v1, 4, v165
	v_add3_u32 v169, 0, v0, v1
	ds_read_b128 v[16:19], v169
	ds_read_b128 v[20:23], v169 offset:32
	ds_read_b128 v[24:27], v169 offset:6656
	ds_read_b128 v[28:31], v169 offset:6688
	v_lshlrev_b32_e32 v167, 4, v165
	s_waitcnt lgkmcnt(3)
	v_mfma_f32_32x32x16_bf16 v[0:15], v[16:19], v[100:103], v[42:57]
	ds_read_b128 v[16:19], v169 offset:64
	ds_read_b128 v[32:35], v169 offset:96
	ds_read_b128 v[36:39], v169 offset:6720
	ds_read_b128 v[58:61], v169 offset:6752
	s_waitcnt lgkmcnt(6)
	v_mfma_f32_32x32x16_bf16 v[0:15], v[20:23], v[96:99], v[0:15]
	s_waitcnt lgkmcnt(5)
	v_mfma_f32_32x32x16_bf16 v[42:57], v[24:27], v[100:103], v[42:57]
	s_waitcnt lgkmcnt(4)
	v_mfma_f32_32x32x16_bf16 v[42:57], v[28:31], v[96:99], v[42:57]
	s_waitcnt lgkmcnt(3)
	v_mfma_f32_32x32x16_bf16 v[0:15], v[16:19], v[92:95], v[0:15]
	ds_read_b128 v[16:19], v169 offset:128
	ds_read_b128 v[20:23], v169 offset:160
	ds_read_b128 v[24:27], v169 offset:6784
	ds_read_b128 v[28:31], v169 offset:6816
	s_waitcnt lgkmcnt(5)
	v_mfma_f32_32x32x16_bf16 v[42:57], v[36:39], v[92:95], v[42:57]
	v_mfma_f32_32x32x16_bf16 v[0:15], v[32:35], v[88:91], v[0:15]
	s_waitcnt lgkmcnt(4)
	v_mfma_f32_32x32x16_bf16 v[42:57], v[58:61], v[88:91], v[42:57]
	s_waitcnt lgkmcnt(3)
	v_mfma_f32_32x32x16_bf16 v[0:15], v[16:19], v[84:87], v[0:15]
	v_mad_u32_u24 v170, v134, s57, v167
	v_add_u32_e32 v16, 0x6800, v170
	ds_read_b128 v[116:119], v16
	ds_read_b128 v[112:115], v16 offset:32
	ds_read_b128 v[140:143], v16 offset:64
	ds_read_b128 v[124:127], v16 offset:96
	ds_read_b128 v[144:147], v16 offset:4608
	ds_read_b128 v[150:153], v16 offset:4640
	ds_read_b128 v[154:157], v16 offset:4672
	ds_read_b128 v[120:123], v16 offset:4704
	s_waitcnt lgkmcnt(9)
	v_mfma_f32_32x32x16_bf16 v[42:57], v[24:27], v[84:87], v[42:57]
	v_mfma_f32_32x32x16_bf16 v[0:15], v[20:23], v[80:83], v[0:15]
	s_waitcnt lgkmcnt(8)
	v_mfma_f32_32x32x16_bf16 v[42:57], v[28:31], v[80:83], v[42:57]
	s_nop 11
	v_max_f32_e32 v16, v42, v42
	v_max_f32_e32 v17, v0, v0
	v_max_f32_e32 v16, v17, v16
	v_max_f32_e32 v17, v43, v43
	v_max_f32_e32 v18, v1, v1
	v_max_f32_e32 v17, v18, v17
	v_max_f32_e32 v18, v45, v45
	v_max_f32_e32 v19, v3, v3
	v_max_f32_e32 v18, v19, v18
	v_max3_f32 v19, v2, v44, v6
	v_max3_f32 v18, v18, v7, v49
	v_max3_f32 v16, v16, v4, v46
	v_max3_f32 v17, v17, v5, v47
	v_max3_f32 v19, v19, v48, v10
	v_max3_f32 v18, v18, v11, v53
	v_max3_f32 v16, v16, v8, v50
	v_max3_f32 v17, v17, v9, v51
	v_max3_f32 v19, v19, v52, v14
	v_max3_f32 v18, v18, v15, v57
	v_max3_f32 v16, v16, v12, v54
	v_max3_f32 v17, v17, v13, v55
	v_max3_f32 v18, v19, v56, v18
	v_max3_f32 v16, v16, v17, v18
	v_mov_b32_e32 v17, v16
	s_nop 1
	v_permlane32_swap_b32_e32 v16, v17
	v_max_f32_e32 v17, v17, v17
	v_max_f32_e32 v16, v16, v16
	v_max_f32_e32 v148, v16, v17
	v_exp_f32_e64 v16, -v148
	v_sub_f32_e32 v0, v0, v148
	v_sub_f32_e32 v1, v1, v148
	v_sub_f32_e32 v2, v2, v148
	v_sub_f32_e32 v3, v3, v148
	v_sub_f32_e32 v4, v4, v148
	v_sub_f32_e32 v5, v5, v148
	v_sub_f32_e32 v6, v6, v148
	v_sub_f32_e32 v7, v7, v148
	v_sub_f32_e32 v174, v48, v148
	v_sub_f32_e32 v175, v49, v148
	v_sub_f32_e32 v176, v50, v148
	v_sub_f32_e32 v177, v51, v148
	v_exp_f32_e32 v48, v0
	v_exp_f32_e32 v49, v1
	v_exp_f32_e32 v50, v2
	v_exp_f32_e32 v51, v3
	v_exp_f32_e32 v128, v4
	v_exp_f32_e32 v129, v5
	v_exp_f32_e32 v130, v6
	v_exp_f32_e32 v131, v7
	v_mul_f32_e32 v58, 0, v16
	v_sub_f32_e32 v8, v8, v148
	v_sub_f32_e32 v9, v9, v148
	v_sub_f32_e32 v10, v10, v148
	v_sub_f32_e32 v11, v11, v148
	v_sub_f32_e32 v12, v12, v148
	v_mov_b32_e32 v59, v58
	v_mov_b32_e32 v60, v58
	v_mov_b32_e32 v61, v58
	v_mov_b32_e32 v62, v58
	v_mov_b32_e32 v63, v58
	v_mov_b32_e32 v64, v58
	v_mov_b32_e32 v65, v58
	v_mov_b32_e32 v66, v58
	v_mov_b32_e32 v67, v58
	v_mov_b32_e32 v68, v58
	v_mov_b32_e32 v69, v58
	v_mov_b32_e32 v70, v58
	v_mov_b32_e32 v71, v58
	v_mov_b32_e32 v72, v58
	v_mov_b32_e32 v73, v58
	v_sub_f32_e32 v161, v42, v148
	v_sub_f32_e32 v171, v43, v148
	v_sub_f32_e32 v172, v44, v148
	v_sub_f32_e32 v173, v45, v148
	v_cvt_pk_bf16_f32 v42, v48, v49
	v_cvt_pk_bf16_f32 v43, v50, v51
	v_cvt_pk_bf16_f32 v44, v128, v129
	v_cvt_pk_bf16_f32 v45, v130, v131
	v_sub_f32_e32 v158, v13, v148
	v_sub_f32_e32 v159, v14, v148
	v_sub_f32_e32 v160, v15, v148
	v_sub_f32_e32 v178, v52, v148
	s_waitcnt lgkmcnt(7)
	v_mfma_f32_32x32x16_bf16 v[16:31], v[116:119], v[42:45], v[58:73]
	v_sub_f32_e32 v179, v53, v148
	v_exp_f32_e32 v52, v8
	v_exp_f32_e32 v53, v9
	v_exp_f32_e32 v116, v10
	v_exp_f32_e32 v117, v11
	v_exp_f32_e32 v118, v12
	v_mov_b64_e32 v[0:1], v[58:59]
	v_mov_b64_e32 v[2:3], v[60:61]
	v_mov_b64_e32 v[4:5], v[62:63]
	v_mov_b64_e32 v[6:7], v[64:65]
	v_mov_b64_e32 v[8:9], v[66:67]
	v_mov_b64_e32 v[10:11], v[68:69]
	v_mov_b64_e32 v[12:13], v[70:71]
	v_mov_b64_e32 v[14:15], v[72:73]
	v_exp_f32_e32 v119, v158
	v_exp_f32_e32 v60, v159
	s_waitcnt lgkmcnt(3)
	v_mfma_f32_32x32x16_bf16 v[0:15], v[144:147], v[42:45], v[0:15]
	v_exp_f32_e32 v61, v160
	v_cvt_pk_bf16_f32 v42, v52, v53
	v_cvt_pk_bf16_f32 v43, v116, v117
	v_cvt_pk_bf16_f32 v44, v118, v119
	v_cvt_pk_bf16_f32 v45, v60, v61
	v_sub_f32_e32 v46, v46, v148
	v_sub_f32_e32 v47, v47, v148
	v_mfma_f32_32x32x16_bf16 v[16:31], v[112:115], v[42:45], v[16:31]
	v_sub_f32_e32 v59, v54, v148
	v_sub_f32_e32 v71, v55, v148
	v_exp_f32_e32 v54, v161
	v_exp_f32_e32 v55, v171
	v_exp_f32_e32 v62, v172
	v_exp_f32_e32 v63, v173
	v_exp_f32_e32 v64, v46
	s_waitcnt lgkmcnt(2)
	v_mfma_f32_32x32x16_bf16 v[0:15], v[150:153], v[42:45], v[0:15]
	v_exp_f32_e32 v65, v47
	v_exp_f32_e32 v66, v174
	v_exp_f32_e32 v67, v175
	v_cvt_pk_bf16_f32 v42, v54, v55
	v_cvt_pk_bf16_f32 v43, v62, v63
	v_cvt_pk_bf16_f32 v44, v64, v65
	v_cvt_pk_bf16_f32 v45, v66, v67
	v_sub_f32_e32 v46, v56, v148
	v_sub_f32_e32 v47, v57, v148
	v_mfma_f32_32x32x16_bf16 v[16:31], v[140:143], v[42:45], v[16:31]
	v_exp_f32_e32 v56, v176
	v_exp_f32_e32 v57, v177
	v_exp_f32_e32 v68, v178
	v_exp_f32_e32 v69, v179
	v_exp_f32_e32 v70, v59
	v_exp_f32_e32 v71, v71
	v_exp_f32_e32 v72, v46
	s_waitcnt lgkmcnt(1)
	v_mfma_f32_32x32x16_bf16 v[0:15], v[154:157], v[42:45], v[0:15]
	v_exp_f32_e32 v73, v47
	v_cvt_pk_bf16_f32 v112, v56, v57
	v_cvt_pk_bf16_f32 v113, v68, v69
	v_cvt_pk_bf16_f32 v114, v70, v71
	v_cvt_pk_bf16_f32 v115, v72, v73
	v_add_f32_e32 v168, 0, v148
	v_xor_b32_e32 v32, 0x80000000, v168
	v_mfma_f32_32x32x16_bf16 v[16:31], v[124:127], v[112:115], v[16:31]
	v_mov_b32_e32 v33, v32
	v_mov_b32_e32 v34, v32
	v_mov_b32_e32 v35, v32
	v_mov_b32_e32 v36, v32
	v_mov_b32_e32 v37, v32
	v_mov_b32_e32 v38, v32
	v_mov_b32_e32 v39, v32
	s_waitcnt lgkmcnt(0)
	v_mfma_f32_32x32x16_bf16 v[0:15], v[120:123], v[112:115], v[0:15]
	v_mov_b32_e32 v40, v32
	v_mov_b32_e32 v41, v32
	v_mov_b32_e32 v42, v32
	v_mov_b32_e32 v43, v32
	v_mov_b32_e32 v44, v32
	v_mov_b32_e32 v45, v32
	v_mov_b32_e32 v46, v32
	v_mov_b32_e32 v47, v32
	s_and_saveexec_b64 s[42:43], s[6:7]
	s_cbranch_execz .LBB0_877
	v_add_u32_e32 v59, v136, v135
	v_mul_lo_u32 v112, v59, 12
	v_sub_u32_e32 v112, v133, v112
	v_mul_lo_u32 v59, v59, s56
	v_lshlrev_b32_e32 v112, 4, v112
	v_add3_u32 v59, 0, v59, v112
	s_waitcnt vmcnt(1)
	ds_write_b128 v59, v[104:107] offset:13312

; #define AT_QK_LD0(kb_) do { if constexpr (NEGM) { const LAS unsigned char* kbp_ = Kl + (kb_) * KBUF + r32 * KROWB + hi * 16; AT_KLD2(0); __builtin_amdgcn_sched_barrier(0); } } while (0)
; template <int DQK, int DV, int RH, bool NEGM> ...
;     ...
;     const int NT = nkv / 64;
;     AT_GLOAD(0); AT_LSTORE(0, 0); __syncthreads();
;     int vs_prev = 2, vs_cur = 0, vs_next = 1;
;     if (!grpB) {
;         for (int t = 0; t < NT; ++t) {
;             const int kb = t & 1;
;             if (t + 1 < NT) AT_GLOAD(t + 1);
;             f32x16 p[RH][2];
;             AT_QK_LD0(kb); AT_QK(kb); AT_VLOAD(vs_cur); AT_SOFTMAX(); AT_PV(vs_cur);
;             if (t + 1 < NT) AT_LSTORE(kb ^ 1, vs_next);
;             __syncthreads();
;             vs_prev = vs_cur; vs_cur = vs_next; vs_next = (vs_next == 2) ? 0 : vs_next + 1;
;         }
.LBB0_881:
	s_or_b64 exec, exec, s[42:43]
	v_pk_add_f32 v[48:49], v[48:49], v[54:55]
	v_pk_add_f32 v[64:65], v[128:129], v[64:65]
	v_pk_add_f32 v[48:49], v[58:59], v[48:49] op_sel_hi:[0,1]
	v_pk_add_f32 v[52:53], v[52:53], v[56:57]
	v_pk_add_f32 v[48:49], v[64:65], v[48:49]
	v_pk_add_f32 v[70:71], v[118:119], v[70:71]
	v_pk_add_f32 v[48:49], v[52:53], v[48:49]
	v_add_u32_e32 v54, v136, v135
	v_pk_add_f32 v[150:151], v[70:71], v[48:49]
	v_add_u32_e32 v48, 0x8c00, v166
	s_waitcnt vmcnt(0)
	ds_write2_b64 v48, v[74:75], v[76:77] offset1:2
	v_mul_lo_u32 v48, v54, 12
	v_sub_u32_e32 v52, v133, v48
	s_lshr_b32 s21, s61, 4
	v_lshlrev_b32_e32 v48, 3, v52
	v_lshlrev_b32_e32 v175, 4, v52
	v_mov_b64_e32 v[52:53], s[40:41]
	s_and_b32 s42, s21, 7
	v_mul_lo_u32 v174, v54, s56
	v_mad_i64_i32 v[54:55], s[40:41], v54, s51, v[52:53]
	v_pk_add_f32 v[50:51], v[50:51], v[62:63]
	v_ashrrev_i32_e32 v49, 31, v48
	v_mad_u64_u32 v[54:55], s[40:41], s42, v163, v[54:55]
	v_pk_add_f32 v[66:67], v[130:131], v[66:67]
	v_pk_add_f32 v[50:51], v[58:59], v[50:51] op_sel_hi:[0,1]
	v_lshl_add_u64 v[48:49], v[48:49], 1, v[54:55]
	v_pk_add_f32 v[56:57], v[116:117], v[68:69]
	v_pk_add_f32 v[50:51], v[66:67], v[50:51]
	v_lshl_add_u64 v[154:155], s[28:29], 0, v[48:49]
	v_mad_i64_i32 v[48:49], s[40:41], v59, s51, v[52:53]
	v_pk_add_f32 v[60:61], v[60:61], v[72:73]
	v_pk_add_f32 v[50:51], v[56:57], v[50:51]
	s_lshl_b32 s43, s42, 6
	v_mad_u64_u32 v[48:49], s[40:41], s42, v163, v[48:49]
	v_pk_add_f32 v[152:153], v[60:61], v[50:51]
	v_lshlrev_b32_e32 v50, 3, v112
	s_add_i32 s40, s47, s43
	v_ashrrev_i32_e32 v51, 31, v50
	s_ashr_i32 s41, s40, 31
	v_lshl_add_u64 v[48:49], v[50:51], 1, v[48:49]
	s_lshl_b64 s[40:41], s[40:41], 13
	v_and_b32_e32 v50, 7, v132
	v_lshl_add_u64 v[156:157], s[28:29], 0, v[48:49]
	v_lshl_add_u64 v[48:49], v[78:79], 0, s[40:41]
	v_lshlrev_b32_e32 v148, 4, v50
	v_lshl_add_u64 v[48:49], v[48:49], 0, v[148:149]
	v_mul_u32_u24_e32 v173, 0x90, v134
	s_mov_b32 s21, 1
	v_lshl_add_u64 v[158:159], s[30:31], 0, v[48:49]
	s_mov_b32 s42, 2
	s_mov_b32 s43, 1
	s_waitcnt lgkmcnt(0)
	s_barrier
	s_mov_b32 s41, 0
	s_branch .Lmla_top1

.Lmla_top1:
	global_load_dwordx4 v[104:107], v[154:155], off
	s_mov_b64 exec, s[8:9]
	global_load_dwordx4 v[108:111], v[156:157], off
	s_mov_b64 exec, -1
	global_load_dwordx4 v[112:115], v[158:159], off
	s_xor_b32 s41, s41, 0x3400
	v_add_u32_e32 v140, s41, v169
	ds_read_b128 v[48:51], v140
	ds_read_b128 v[52:55], v140 offset:32
	ds_read_b128 v[116:119], v140 offset:6656
	ds_read_b128 v[120:123], v140 offset:6688
	s_waitcnt lgkmcnt(3)
	v_mfma_f32_32x32x16_bf16 v[64:79], v[48:51], v[100:103], v[32:47]
	ds_read_b128 v[124:127], v140 offset:64
	ds_read_b128 v[128:131], v140 offset:96
	ds_read_b128 v[132:135], v140 offset:6720
	ds_read_b128 v[136:139], v140 offset:6752
	s_waitcnt lgkmcnt(4)
	v_mfma_f32_32x32x16_bf16 v[64:79], v[52:55], v[96:99], v[64:79]
	v_mfma_f32_32x32x16_bf16 v[48:63], v[116:119], v[100:103], v[32:47]
	v_mfma_f32_32x32x16_bf16 v[48:63], v[120:123], v[96:99], v[48:63]
	s_waitcnt lgkmcnt(1)
	v_mfma_f32_32x32x16_bf16 v[64:79], v[124:127], v[92:95], v[64:79]
	v_mfma_f32_32x32x16_bf16 v[48:63], v[132:135], v[92:95], v[48:63]
	v_mfma_f32_32x32x16_bf16 v[64:79], v[128:131], v[88:91], v[64:79]
	ds_read_b128 v[116:119], v140 offset:128
	ds_read_b128 v[120:123], v140 offset:160
	ds_read_b128 v[128:131], v140 offset:6784
	ds_read_b128 v[176:179], v140 offset:6816
	s_waitcnt lgkmcnt(3)
	v_mfma_f32_32x32x16_bf16 v[48:63], v[136:139], v[88:91], v[48:63]
	v_mfma_f32_32x32x16_bf16 v[64:79], v[116:119], v[84:87], v[64:79]
	s_mulk_i32 s21, 0x2400
	v_add_u32_e32 v116, s21, v170
	ds_read_b128 v[136:139], v116 offset:26624
	ds_read_b128 v[124:127], v116 offset:26656
	s_waitcnt lgkmcnt(3)
	v_mfma_f32_32x32x16_bf16 v[48:63], v[128:131], v[84:87], v[48:63]
	v_mfma_f32_32x32x16_bf16 v[64:79], v[120:123], v[80:83], v[64:79]
	ds_read_b128 v[132:135], v116 offset:26688
	ds_read_b128 v[120:123], v116 offset:26720
	ds_read_b128 v[144:147], v116 offset:31232
	ds_read_b128 v[140:143], v116 offset:31264
	ds_read_b128 v[128:131], v116 offset:31296
	ds_read_b128 v[116:119], v116 offset:31328
	s_waitcnt lgkmcnt(8)
	v_mfma_f32_32x32x16_bf16 v[48:63], v[176:179], v[80:83], v[48:63]
	s_add_i32 s43, s43, 1
	s_sub_i32 s21, 0x3400, s41
	v_lshl_add_u64 v[154:155], v[154:155], 0, s[34:35]
	v_lshl_add_u64 v[156:157], v[156:157], 0, s[34:35]
	v_lshl_add_u64 v[158:159], v[158:159], 0, s[36:37]
	s_nop 7
	v_max_f32_e32 v148, v64, v48
	v_max_f32_e32 v160, v65, v49
	v_max_f32_e32 v161, v67, v51
	v_max3_f32 v176, v66, v50, v70
	v_max3_f32 v161, v161, v71, v55
	v_max3_f32 v148, v148, v68, v52
	v_max3_f32 v160, v160, v69, v53
	v_max3_f32 v176, v176, v54, v74
	v_max3_f32 v161, v161, v75, v59
	v_max3_f32 v148, v148, v72, v56
	v_max3_f32 v160, v160, v73, v57
	v_max3_f32 v176, v176, v58, v78
	v_max3_f32 v161, v161, v79, v63
	v_max3_f32 v148, v148, v76, v60
	v_max3_f32 v160, v160, v77, v61
	v_max3_f32 v161, v176, v62, v161
	v_max3_f32 v148, v148, v160, v161
	v_mov_b32_e32 v160, v148
	s_nop 1
	v_permlane32_swap_b32_e32 v148, v160
	v_max_f32_e32 v148, v148, v160
	v_cmp_lt_f32_e32 vcc, s59, v148
	s_cbranch_vccz .Lmla_norescale
	v_max_f32_e32 v32, v148, v148
	v_max_f32_e32 v148, 0, v32
	v_exp_f32_e64 v160, -v148
	v_add_f32_e32 v168, v168, v148
	v_xor_b32_e32 v32, 0x80000000, v168
	v_mov_b32_e32 v33, v32
	v_mov_b32_e32 v34, v32
	v_mov_b32_e32 v35, v32
	v_mov_b32_e32 v36, v32
	v_mov_b32_e32 v37, v32
	v_mov_b32_e32 v38, v32
	v_mov_b32_e32 v39, v32
	v_mov_b32_e32 v40, v32
	v_mov_b32_e32 v41, v32
	v_mov_b32_e32 v42, v32
	v_mov_b32_e32 v43, v32
	v_mov_b32_e32 v44, v32
	v_mov_b32_e32 v45, v32
	v_mov_b32_e32 v46, v32
	v_mov_b32_e32 v47, v32
	v_pk_add_f32 v[64:65], v[64:65], v[148:149] op_sel_hi:[1,0] neg_lo:[0,1] neg_hi:[0,1]
	v_pk_add_f32 v[48:49], v[48:49], v[148:149] op_sel_hi:[1,0] neg_lo:[0,1] neg_hi:[0,1]
	v_pk_add_f32 v[66:67], v[66:67], v[148:149] op_sel_hi:[1,0] neg_lo:[0,1] neg_hi:[0,1]
	v_pk_add_f32 v[50:51], v[50:51], v[148:149] op_sel_hi:[1,0] neg_lo:[0,1] neg_hi:[0,1]
	v_pk_add_f32 v[68:69], v[68:69], v[148:149] op_sel_hi:[1,0] neg_lo:[0,1] neg_hi:[0,1]
	v_pk_add_f32 v[52:53], v[52:53], v[148:149] op_sel_hi:[1,0] neg_lo:[0,1] neg_hi:[0,1]
	v_pk_add_f32 v[70:71], v[70:71], v[148:149] op_sel_hi:[1,0] neg_lo:[0,1] neg_hi:[0,1]
	v_pk_add_f32 v[54:55], v[54:55], v[148:149] op_sel_hi:[1,0] neg_lo:[0,1] neg_hi:[0,1]
	v_pk_add_f32 v[72:73], v[72:73], v[148:149] op_sel_hi:[1,0] neg_lo:[0,1] neg_hi:[0,1]
	v_pk_add_f32 v[56:57], v[56:57], v[148:149] op_sel_hi:[1,0] neg_lo:[0,1] neg_hi:[0,1]
	v_pk_add_f32 v[74:75], v[74:75], v[148:149] op_sel_hi:[1,0] neg_lo:[0,1] neg_hi:[0,1]
	v_pk_add_f32 v[58:59], v[58:59], v[148:149] op_sel_hi:[1,0] neg_lo:[0,1] neg_hi:[0,1]
	v_pk_add_f32 v[76:77], v[76:77], v[148:149] op_sel_hi:[1,0] neg_lo:[0,1] neg_hi:[0,1]
	v_pk_add_f32 v[60:61], v[60:61], v[148:149] op_sel_hi:[1,0] neg_lo:[0,1] neg_hi:[0,1]
	v_pk_add_f32 v[78:79], v[78:79], v[148:149] op_sel_hi:[1,0] neg_lo:[0,1] neg_hi:[0,1]
	v_pk_add_f32 v[62:63], v[62:63], v[148:149] op_sel_hi:[1,0] neg_lo:[0,1] neg_hi:[0,1]
	v_pk_mul_f32 v[30:31], v[30:31], v[160:161] op_sel_hi:[1,0]
	v_pk_mul_f32 v[28:29], v[28:29], v[160:161] op_sel_hi:[1,0]
	v_pk_mul_f32 v[26:27], v[26:27], v[160:161] op_sel_hi:[1,0]
	v_pk_mul_f32 v[24:25], v[24:25], v[160:161] op_sel_hi:[1,0]
	v_pk_mul_f32 v[22:23], v[22:23], v[160:161] op_sel_hi:[1,0]
	v_pk_mul_f32 v[20:21], v[20:21], v[160:161] op_sel_hi:[1,0]
	v_pk_mul_f32 v[18:19], v[18:19], v[160:161] op_sel_hi:[1,0]
	v_pk_mul_f32 v[16:17], v[16:17], v[160:161] op_sel_hi:[1,0]
	v_pk_mul_f32 v[14:15], v[14:15], v[160:161] op_sel_hi:[1,0]
	v_pk_mul_f32 v[12:13], v[12:13], v[160:161] op_sel_hi:[1,0]
	v_pk_mul_f32 v[10:11], v[10:11], v[160:161] op_sel_hi:[1,0]
	v_pk_mul_f32 v[8:9], v[8:9], v[160:161] op_sel_hi:[1,0]
	v_pk_mul_f32 v[6:7], v[6:7], v[160:161] op_sel_hi:[1,0]
	v_pk_mul_f32 v[4:5], v[4:5], v[160:161] op_sel_hi:[1,0]
	v_pk_mul_f32 v[2:3], v[2:3], v[160:161] op_sel_hi:[1,0]
	v_pk_mul_f32 v[0:1], v[0:1], v[160:161] op_sel_hi:[1,0]
	v_pk_mul_f32 v[152:153], v[152:153], v[160:161] op_sel_hi:[1,0]
	v_pk_mul_f32 v[150:151], v[150:151], v[160:161] op_sel_hi:[1,0]
.Lmla_norescale:
	v_exp_f32_e32 v160, v64
	v_exp_f32_e32 v161, v65
	v_exp_f32_e32 v64, v66
	v_exp_f32_e32 v65, v67
	v_exp_f32_e32 v68, v68
	v_exp_f32_e32 v69, v69
	v_exp_f32_e32 v66, v70
	v_exp_f32_e32 v67, v71
	v_cvt_pk_bf16_f32 v176, v160, v161
	v_cvt_pk_bf16_f32 v177, v64, v65
	v_cvt_pk_bf16_f32 v178, v68, v69
	v_cvt_pk_bf16_f32 v179, v66, v67
	v_exp_f32_e32 v70, v74
	v_exp_f32_e32 v71, v75
	s_waitcnt lgkmcnt(0)
	v_mfma_f32_32x32x16_bf16 v[16:31], v[136:139], v[176:179], v[16:31]
	v_exp_f32_e32 v136, v72
	v_exp_f32_e32 v137, v73
	v_exp_f32_e32 v74, v76
	v_exp_f32_e32 v75, v77
	v_exp_f32_e32 v72, v78
	v_exp_f32_e32 v73, v79
	v_exp_f32_e32 v76, v48
	v_mfma_f32_32x32x16_bf16 v[0:15], v[144:147], v[176:179], v[0:15]
	v_cvt_pk_bf16_f32 v144, v136, v137
	v_cvt_pk_bf16_f32 v145, v70, v71
	v_cvt_pk_bf16_f32 v146, v74, v75
	v_cvt_pk_bf16_f32 v147, v72, v73
	v_exp_f32_e32 v77, v49
	v_exp_f32_e32 v48, v50
	v_exp_f32_e32 v49, v51
	v_mfma_f32_32x32x16_bf16 v[16:31], v[124:127], v[144:147], v[16:31]
	v_exp_f32_e32 v52, v52
	v_exp_f32_e32 v53, v53
	v_exp_f32_e32 v50, v54
	v_exp_f32_e32 v51, v55
	v_cvt_pk_bf16_f32 v124, v76, v77
	v_cvt_pk_bf16_f32 v125, v48, v49
	v_cvt_pk_bf16_f32 v126, v52, v53
	v_mfma_f32_32x32x16_bf16 v[0:15], v[140:143], v[144:147], v[0:15]
	v_cvt_pk_bf16_f32 v127, v50, v51
	v_exp_f32_e32 v78, v56
	v_exp_f32_e32 v79, v57
	v_exp_f32_e32 v54, v58
	v_exp_f32_e32 v55, v59
	v_exp_f32_e32 v58, v60
	v_exp_f32_e32 v59, v61
	v_mfma_f32_32x32x16_bf16 v[16:31], v[132:135], v[124:127], v[16:31]
	v_exp_f32_e32 v56, v62
	v_exp_f32_e32 v57, v63
	v_cvt_pk_bf16_f32 v60, v78, v79
	v_cvt_pk_bf16_f32 v61, v54, v55
	v_cvt_pk_bf16_f32 v62, v58, v59
	v_cvt_pk_bf16_f32 v63, v56, v57
	v_mfma_f32_32x32x16_bf16 v[0:15], v[128:131], v[124:127], v[0:15]
	v_mfma_f32_32x32x16_bf16 v[16:31], v[120:123], v[60:63], v[16:31]
	v_mfma_f32_32x32x16_bf16 v[0:15], v[116:119], v[60:63], v[0:15]
	v_add3_u32 v241, s21, v174, v175
	s_waitcnt vmcnt(1)
	ds_write_b128 v241, v[104:107]
	s_mov_b64 exec, s[8:9]
	v_add3_u32 v241, s21, v171, v172
	ds_write_b128 v241, v[108:111]
	s_mov_b64 exec, -1
	v_pk_add_f32 v[48:49], v[64:65], v[48:49]
	v_pk_add_f32 v[60:61], v[160:161], v[76:77]
	v_pk_add_f32 v[48:49], v[152:153], v[48:49]
	v_pk_add_f32 v[50:51], v[66:67], v[50:51]
	v_pk_add_f32 v[60:61], v[150:151], v[60:61]
	v_pk_add_f32 v[52:53], v[68:69], v[52:53]
	v_pk_add_f32 v[48:49], v[50:51], v[48:49]
	v_pk_add_f32 v[50:51], v[70:71], v[54:55]
	v_pk_add_f32 v[52:53], v[52:53], v[60:61]
	v_pk_add_f32 v[60:61], v[136:137], v[78:79]
	v_pk_add_f32 v[48:49], v[50:51], v[48:49]
	v_pk_add_f32 v[50:51], v[72:73], v[56:57]
	s_mul_i32 s21, s42, 0x2400
	s_add_i32 s40, s42, 1
	v_pk_add_f32 v[52:53], v[60:61], v[52:53]
	v_pk_add_f32 v[58:59], v[74:75], v[58:59]
	v_pk_add_f32 v[152:153], v[50:51], v[48:49]
	v_add_u32_e32 v48, s21, v243
	s_cmp_lg_u32 s42, 2
	v_pk_add_f32 v[150:151], v[58:59], v[52:53]
	s_cselect_b32 s40, s40, 0
	s_cmp_lg_u32 s43, 63
	s_waitcnt vmcnt(0)
	ds_write2_b64 v48, v[112:113], v[114:115] offset1:2
	s_waitcnt lgkmcnt(0)
	s_barrier
	s_cbranch_scc1 .Lmla_loop
	ds_read_b128 v[64:67], v169 offset:13312
	ds_read_b128 v[68:71], v169 offset:13344
	ds_read_b128 v[72:75], v169 offset:19968
	ds_read_b128 v[76:79], v169 offset:20000
	s_waitcnt lgkmcnt(3)
	v_mfma_f32_32x32x16_bf16 v[48:63], v[64:67], v[100:103], v[32:47]
	ds_read_b128 v[64:67], v169 offset:13376
	ds_read_b128 v[104:107], v169 offset:13408
	ds_read_b128 v[108:111], v169 offset:20032
	ds_read_b128 v[112:115], v169 offset:20064
	s_waitcnt lgkmcnt(6)
	v_mfma_f32_32x32x16_bf16 v[48:63], v[68:71], v[96:99], v[48:63]
	s_waitcnt lgkmcnt(5)
	v_mfma_f32_32x32x16_bf16 v[32:47], v[72:75], v[100:103], v[32:47]
	s_waitcnt lgkmcnt(4)
	v_mfma_f32_32x32x16_bf16 v[32:47], v[76:79], v[96:99], v[32:47]
	s_waitcnt lgkmcnt(3)
	v_mfma_f32_32x32x16_bf16 v[48:63], v[64:67], v[92:95], v[48:63]
	ds_read_b128 v[64:67], v169 offset:13440
	ds_read_b128 v[68:71], v169 offset:13472
	ds_read_b128 v[72:75], v169 offset:20096
	ds_read_b128 v[76:79], v169 offset:20128
	s_waitcnt lgkmcnt(5)
	v_mfma_f32_32x32x16_bf16 v[32:47], v[108:111], v[92:95], v[32:47]
	v_mfma_f32_32x32x16_bf16 v[48:63], v[104:107], v[88:91], v[48:63]
	s_waitcnt lgkmcnt(4)
	v_mfma_f32_32x32x16_bf16 v[32:47], v[112:115], v[88:91], v[32:47]
	s_waitcnt lgkmcnt(3)
	v_mfma_f32_32x32x16_bf16 v[48:63], v[64:67], v[84:87], v[48:63]
	v_add3_u32 v64, v167, s21, v173
	v_add_u32_e32 v65, 0x6800, v64
	ds_read_b128 v[108:111], v65
	ds_read_b128 v[104:107], v65 offset:32
	ds_read_b128 v[96:99], v65 offset:64
	ds_read_b128 v[88:91], v65 offset:96
	s_waitcnt lgkmcnt(5)
	v_mfma_f32_32x32x16_bf16 v[32:47], v[72:75], v[84:87], v[32:47]
	ds_read_b128 v[112:115], v65 offset:4608
	ds_read_b128 v[100:103], v65 offset:4640
	ds_read_b128 v[92:95], v65 offset:4672
	ds_read_b128 v[84:87], v65 offset:4704
	v_mfma_f32_32x32x16_bf16 v[48:63], v[68:71], v[80:83], v[48:63]
	s_waitcnt lgkmcnt(8)
	v_mfma_f32_32x32x16_bf16 v[32:47], v[76:79], v[80:83], v[32:47]
	s_nop 11
	v_max_f32_e32 v64, v32, v32
	v_max_f32_e32 v65, v48, v48
	v_max_f32_e32 v64, v65, v64
	v_max_f32_e32 v65, v33, v33
	v_max_f32_e32 v66, v49, v49
	v_max_f32_e32 v65, v66, v65
	v_max_f32_e32 v66, v35, v35
	v_max_f32_e32 v67, v51, v51
	v_max_f32_e32 v66, v67, v66
	v_max3_f32 v67, v50, v34, v54
	v_max3_f32 v66, v66, v55, v39
	v_max3_f32 v64, v64, v52, v36
	v_max3_f32 v65, v65, v53, v37
	v_max3_f32 v67, v67, v38, v58
	v_max3_f32 v66, v66, v59, v43
	v_max3_f32 v64, v64, v56, v40
	v_max3_f32 v65, v65, v57, v41
	v_max3_f32 v67, v67, v42, v62
	v_max3_f32 v66, v66, v63, v47
	v_max3_f32 v64, v64, v60, v44
	v_max3_f32 v65, v65, v61, v45
	v_max3_f32 v66, v67, v46, v66
	v_max3_f32 v64, v64, v65, v66
	v_mov_b32_e32 v65, v64
	s_nop 1
	v_permlane32_swap_b32_e32 v64, v65
	v_max_f32_e32 v65, v65, v65
	v_max_f32_e32 v64, v64, v64
	v_max_f32_e32 v64, v64, v65
	v_cmp_lt_f32_e32 vcc, s59, v64
	s_cbranch_vccnz .LBB0_861
	v_mov_b32_e32 v64, v151
	v_mov_b32_e32 v151, v152
	v_mov_b32_e32 v65, v153
	s_branch .LBB0_862

; __global__ void __launch_bounds__(512, 2) fwd_mega(Args a) {
	.amdhsa_kernel _Z8fwd_mega4Args
		.amdhsa_group_segment_fixed_size 0
		.amdhsa_private_segment_fixed_size 0
		.amdhsa_kernarg_size 496
		.amdhsa_user_sgpr_count 2
		.amdhsa_user_sgpr_dispatch_ptr 0
		.amdhsa_user_sgpr_queue_ptr 0
		.amdhsa_user_sgpr_kernarg_segment_ptr 1
		.amdhsa_user_sgpr_dispatch_id 0
		.amdhsa_user_sgpr_kernarg_preload_length 0
		.amdhsa_user_sgpr_kernarg_preload_offset 0
		.amdhsa_user_sgpr_private_segment_size 0
		.amdhsa_uses_dynamic_stack 0
		.amdhsa_enable_private_segment 0
		.amdhsa_system_sgpr_workgroup_id_x 1
		.amdhsa_system_sgpr_workgroup_id_y 0
		.amdhsa_system_sgpr_workgroup_id_z 0
		.amdhsa_system_sgpr_workgroup_info 0
		.amdhsa_system_vgpr_workitem_id 2
		.amdhsa_next_free_vgpr 244
		.amdhsa_next_free_sgpr 98
		.amdhsa_accum_offset 244
		.amdhsa_reserve_vcc 1
		.amdhsa_float_round_mode_32 0
		.amdhsa_float_round_mode_16_64 0
		.amdhsa_float_denorm_mode_32 3
		.amdhsa_float_denorm_mode_16_64 3
		.amdhsa_dx10_clamp 1
		.amdhsa_ieee_mode 1
		.amdhsa_fp16_overflow 0
		.amdhsa_tg_split 0
		.amdhsa_exception_fp_ieee_invalid_op 0
		.amdhsa_exception_fp_denorm_src 0
		.amdhsa_exception_fp_ieee_div_zero 0
		.amdhsa_exception_fp_ieee_overflow 0
		.amdhsa_exception_fp_ieee_underflow 0
		.amdhsa_exception_fp_ieee_inexact 0
		.amdhsa_exception_int_div_zero 0
	.end_amdhsa_kernel

; __global__ void __launch_bounds__(512, 2) fwd_mega(Args a) {
.Lfunc_end0:
	.size	_Z8fwd_mega4Args, .Lfunc_end0-_Z8fwd_mega4Args
	.set _Z8fwd_mega4Args.num_vgpr, 244
	.set _Z8fwd_mega4Args.num_agpr, 0
	.set _Z8fwd_mega4Args.numbered_sgpr, 98
	.set _Z8fwd_mega4Args.num_named_barrier, 0
	.set _Z8fwd_mega4Args.private_seg_size, 0
	.set _Z8fwd_mega4Args.uses_vcc, 1
	.set _Z8fwd_mega4Args.uses_flat_scratch, 0
	.set _Z8fwd_mega4Args.has_dyn_sized_stack, 0
	.set _Z8fwd_mega4Args.has_recursion, 0
	.set _Z8fwd_mega4Args.has_indirect_call, 0

; __global__ void __launch_bounds__(512, 2) fwd_mega(Args a) {
amdhsa.kernels:
  - .agpr_count:     0
    .args:
      - .offset:         0
        .size:           240
        .value_kind:     by_value
      - .offset:         240
        .size:           4
        .value_kind:     hidden_block_count_x
      - .offset:         244
        .size:           4
        .value_kind:     hidden_block_count_y
      - .offset:         248
        .size:           4
        .value_kind:     hidden_block_count_z
      - .offset:         252
        .size:           2
        .value_kind:     hidden_group_size_x
      - .offset:         254
        .size:           2
        .value_kind:     hidden_group_size_y
      - .offset:         256
        .size:           2
        .value_kind:     hidden_group_size_z
      - .offset:         258
        .size:           2
        .value_kind:     hidden_remainder_x
      - .offset:         260
        .size:           2
        .value_kind:     hidden_remainder_y
      - .offset:         262
        .size:           2
        .value_kind:     hidden_remainder_z
      - .offset:         280
        .size:           8
        .value_kind:     hidden_global_offset_x
      - .offset:         288
        .size:           8
        .value_kind:     hidden_global_offset_y
      - .offset:         296
        .size:           8
        .value_kind:     hidden_global_offset_z
      - .offset:         304
        .size:           2
        .value_kind:     hidden_grid_dims
      - .offset:         328
        .size:           8
        .value_kind:     hidden_multigrid_sync_arg
      - .offset:         360
        .size:           4
        .value_kind:     hidden_dynamic_lds_size
    .group_segment_fixed_size: 0
    .kernarg_segment_align: 8
    .kernarg_segment_size: 496
    .language:       OpenCL C
    .language_version:
      - 2
      - 0
    .max_flat_workgroup_size: 512
    .name:           _Z8fwd_mega4Args
    .private_segment_fixed_size: 0
    .sgpr_count:     104
    .sgpr_spill_count: 6
    .symbol:         _Z8fwd_mega4Args.kd
    .uniform_work_group_size: 1
    .uses_dynamic_stack: false
    .vgpr_count:     244
    .vgpr_spill_count: 0
    .wavefront_size: 64
